# seam-hosted W2GU conversion redistributed: four waves per workgroup at seams 0-3 only (was two waves at eight seams)
# speedup vs baseline: 1.0088x; 1.0032x over previous
; #define LAS __attribute__((address_space(3)))
; #define TR_LOAD(p) __builtin_nontemporal_load(p)
; __device__ __forceinline__ TrItem tr_decode(int it, const float* const* in, unsigned char* ws, int lane) {
;     ...
;     const int rh = r >> 3, rl = r & 7, nq = ndb >> DL, kbh = rh / nq, dbh = rh - kbh * nq;
;     const int kb = (kbh << KL) + (rl >> DL), db = (dbh << DL) + (rl & ((1 << DL) - 1)), d0 = db * 64, k0 = kb * 64;
;     ...
;     const int kb = r / ndb, db = r - kb * ndb, d0 = db * 64, k0 = kb * 64;
;     ...
;     const int blk = d0 + 32 * ((lane & 15) >> 3);
;     const float* src = W; int s0 = blk;
;     if (kind == 1) { const int pn = blk >> 8, bj = (blk >> 7) & 1, o = blk & 127; src = bj ? W2 : W; s0 = pn * 128 + o; }
;     else if (kind == 2) s0 = win_src(blk);
;     TrItem t; t.src = src + (size_t)(k0 + (lane >> 4)) * N + s0 + 4 * (lane & 7); t.gain = gain ? gain + k0 + 8 * (lane & 7) : nullptr;
;     t.dst = WT + (size_t)(d0 + (lane >> 3)) * K + k0 + 8 * (lane & 7); t.N = N; t.K = K; t.nts = nts && TR_NTS;
; __device__ __forceinline__ void tr_all(const float* const* in, unsigned char* ws, LAS float* scr, int gw, int ngw, int lane, const TrRanges rg) {
;     ...
;     for (int i = 0; i < 16; ++i) v[i] = TR_LOAD((const f32x4*)(cur.src + (size_t)(4 * i) * cur.N));
;     for (int it = gw; it < TR_CNT; it += ngw) {
;         const int nit = it + ngw; const bool hn = nit < TR_CNT;
;         TrItem nx = cur; f32x4 w[16];
;         if (hn) { nx = tr_decode(rg.item(nit), in, ws, lane);
; #pragma unroll
;             for (int i = 0; i < 16; ++i) w[i] = TR_LOAD((const f32x4*)(nx.src + (size_t)(4 * i) * nx.N)); }
;         LAS float* wp = scr + (lane >> 4) * 65 + 4 * (lane & 15);
; #pragma unroll
;         for (int i = 0; i < 16; ++i) { wp[(4 * i) * 65 + 0] = v[i][0]; wp[(4 * i) * 65 + 1] = v[i][1]; wp[(4 * i) * 65 + 2] = v[i][2]; wp[(4 * i) * 65 + 3] = v[i][3]; }
.Lseam_cv_0:
	s_cmp_lt_u32 s98, 2
	s_cbranch_scc1 .LBB0_339
	s_cmp_gt_u32 s98, 5
	s_cbranch_scc1 .LBB0_339
	s_mov_b64 exec, -1
	s_lshl_b32 s99, s87, 2
	s_add_i32 s99, s99, s98
	s_add_i32 s99, s99, 0x5fe
	s_lshr_b32 s100, s99, 3
	s_mul_i32 s101, s100, 0x5d2
	s_lshr_b32 s101, s101, 16
	s_mul_i32 vcc_lo, s101, 44
	s_sub_i32 s100, s100, vcc_lo
	s_and_b32 vcc_lo, s99, 7
	s_lshr_b32 vcc_hi, vcc_lo, 2
	s_lshl_b32 s101, s101, 1
	s_add_i32 s101, s101, vcc_hi
	s_and_b32 vcc_lo, vcc_lo, 3
	s_lshl_b32 s100, s100, 2
	s_add_i32 s100, s100, vcc_lo
	s_lshl_b32 s101, s101, 6
	s_lshl_b32 s100, s100, 6
	v_and_b32_e32 v66, 63, v1
	v_lshrrev_b32_e32 v67, 4, v66
	v_and_b32_e32 v68, 15, v66
	v_and_b32_e32 v73, 7, v66
	v_lshrrev_b32_e32 v72, 3, v66
	s_mul_i32 s99, s98, 0x4100
	v_mul_u32_u24_e32 v70, 0x104, v67
	v_lshl_add_u32 v70, v68, 4, v70
	v_add_u32_e32 v70, s99, v70
	v_mul_u32_u24_e32 v71, 0x820, v73
	v_lshl_add_u32 v71, v72, 2, v71
	v_add_u32_e32 v71, s99, v71
	s_mul_i32 s99, s101, 0x1600
	s_lshr_b32 vcc_lo, s100, 8
	s_lshl_b32 vcc_lo, vcc_lo, 7
	s_add_i32 s99, s99, vcc_lo
	s_and_b32 vcc_lo, s100, 0x7f
	s_add_i32 s99, s99, vcc_lo
	s_lshl_b32 s99, s99, 2
	v_mul_u32_u24_e32 v69, 0x5800, v67
	v_lshl_add_u32 v69, v68, 4, v69
	v_add_u32_e32 v69, s99, v69
	s_lshl_b32 s99, s100, 12
	s_lshl_b32 vcc_lo, s101, 1
	s_add_i32 s99, s99, vcc_lo
	v_lshlrev_b32_e32 v72, 12, v72
	v_lshl_add_u32 v72, v73, 4, v72
	v_add_u32_e32 v72, s99, v72
	s_lshl_b32 s99, s101, 2
	v_lshlrev_b32_e32 v73, 5, v73
	v_add_u32_e32 v73, s99, v73
	s_nop 0
	s_bitcmp1_b32 s100, 7
	v_readlane_b32 s100, v254, 6
	v_readlane_b32 s101, v254, 7
	v_readlane_b32 s98, v254, 8
	v_readlane_b32 s99, v254, 9
	s_nop 3
	s_cselect_b32 s100, s98, s100
	s_cselect_b32 s101, s99, s101
	v_readlane_b32 s98, v254, 4
	v_readlane_b32 s99, v254, 5
	global_load_dwordx4 v[2:5], v69, s[100:101] nt
	v_add_u32_e32 v68, 0x16000, v69
	global_load_dwordx4 v[6:9], v68, s[100:101] nt
	v_add_u32_e32 v67, 0x2c000, v69
	global_load_dwordx4 v[10:13], v67, s[100:101] nt
	v_add_u32_e32 v68, 0x42000, v69
	global_load_dwordx4 v[14:17], v68, s[100:101] nt
	v_add_u32_e32 v67, 0x58000, v69
	global_load_dwordx4 v[18:21], v67, s[100:101] nt
	v_add_u32_e32 v68, 0x6e000, v69
	global_load_dwordx4 v[22:25], v68, s[100:101] nt
	v_add_u32_e32 v67, 0x84000, v69
	global_load_dwordx4 v[26:29], v67, s[100:101] nt
	v_add_u32_e32 v68, 0x9a000, v69
	global_load_dwordx4 v[30:33], v68, s[100:101] nt
	v_add_u32_e32 v67, 0xb0000, v69
	global_load_dwordx4 v[34:37], v67, s[100:101] nt
	v_add_u32_e32 v68, 0xc6000, v69
	global_load_dwordx4 v[38:41], v68, s[100:101] nt
	v_add_u32_e32 v67, 0xdc000, v69
	global_load_dwordx4 v[42:45], v67, s[100:101] nt
	v_add_u32_e32 v68, 0xf2000, v69
	global_load_dwordx4 v[46:49], v68, s[100:101] nt
	v_add_u32_e32 v67, 0x108000, v69
	global_load_dwordx4 v[50:53], v67, s[100:101] nt
	v_add_u32_e32 v68, 0x11e000, v69
	global_load_dwordx4 v[54:57], v68, s[100:101] nt
	v_add_u32_e32 v67, 0x134000, v69
	global_load_dwordx4 v[58:61], v67, s[100:101] nt
	v_add_u32_e32 v68, 0x14a000, v69
	global_load_dwordx4 v[62:65], v68, s[100:101] nt
	global_load_dwordx4 v[74:77], v73, s[98:99]
	global_load_dwordx4 v[78:81], v73, s[98:99] offset:16
	s_waitcnt vmcnt(17)
	ds_write_b32 v70, v2
	ds_write_b32 v70, v3 offset:4
	ds_write_b32 v70, v4 offset:8
	ds_write_b32 v70, v5 offset:12
	s_waitcnt vmcnt(16)
	ds_write_b32 v70, v6 offset:1040
	ds_write_b32 v70, v7 offset:1044
	ds_write_b32 v70, v8 offset:1048
	ds_write_b32 v70, v9 offset:1052
	s_waitcnt vmcnt(15)
	ds_write_b32 v70, v10 offset:2080
	ds_write_b32 v70, v11 offset:2084
	ds_write_b32 v70, v12 offset:2088
	ds_write_b32 v70, v13 offset:2092
	s_waitcnt vmcnt(14)
	ds_write_b32 v70, v14 offset:3120
	ds_write_b32 v70, v15 offset:3124
	ds_write_b32 v70, v16 offset:3128
	ds_write_b32 v70, v17 offset:3132
	s_waitcnt vmcnt(13)
	ds_write_b32 v70, v18 offset:4160
	ds_write_b32 v70, v19 offset:4164
	ds_write_b32 v70, v20 offset:4168
	ds_write_b32 v70, v21 offset:4172
	s_waitcnt vmcnt(12)
	ds_write_b32 v70, v22 offset:5200
	ds_write_b32 v70, v23 offset:5204
	ds_write_b32 v70, v24 offset:5208
	ds_write_b32 v70, v25 offset:5212
	s_waitcnt vmcnt(11)
	ds_write_b32 v70, v26 offset:6240
	ds_write_b32 v70, v27 offset:6244
	ds_write_b32 v70, v28 offset:6248
	ds_write_b32 v70, v29 offset:6252
	s_waitcnt vmcnt(10)
	ds_write_b32 v70, v30 offset:7280
	ds_write_b32 v70, v31 offset:7284
	ds_write_b32 v70, v32 offset:7288
	ds_write_b32 v70, v33 offset:7292
	s_waitcnt vmcnt(9)
	ds_write_b32 v70, v34 offset:8320
	ds_write_b32 v70, v35 offset:8324
	ds_write_b32 v70, v36 offset:8328
	ds_write_b32 v70, v37 offset:8332
	s_waitcnt vmcnt(8)
	ds_write_b32 v70, v38 offset:9360
	ds_write_b32 v70, v39 offset:9364
	ds_write_b32 v70, v40 offset:9368
	ds_write_b32 v70, v41 offset:9372
	s_waitcnt vmcnt(7)
	ds_write_b32 v70, v42 offset:10400
	ds_write_b32 v70, v43 offset:10404
	ds_write_b32 v70, v44 offset:10408
	ds_write_b32 v70, v45 offset:10412
	s_waitcnt vmcnt(6)
	ds_write_b32 v70, v46 offset:11440
	ds_write_b32 v70, v47 offset:11444
	ds_write_b32 v70, v48 offset:11448
	ds_write_b32 v70, v49 offset:11452
	s_waitcnt vmcnt(5)
	ds_write_b32 v70, v50 offset:12480
	ds_write_b32 v70, v51 offset:12484
	ds_write_b32 v70, v52 offset:12488
	ds_write_b32 v70, v53 offset:12492
	s_waitcnt vmcnt(4)
	ds_write_b32 v70, v54 offset:13520
	ds_write_b32 v70, v55 offset:13524
	ds_write_b32 v70, v56 offset:13528
	ds_write_b32 v70, v57 offset:13532
	s_waitcnt vmcnt(3)
	ds_write_b32 v70, v58 offset:14560
	ds_write_b32 v70, v59 offset:14564
	ds_write_b32 v70, v60 offset:14568
	ds_write_b32 v70, v61 offset:14572
	s_waitcnt vmcnt(2)
; #define LAS __attribute__((address_space(3)))
; __device__ __forceinline__ unsigned cvtpk(float lo, float hi) { f32x2_t v = {lo, hi}; bf16x2_t b = __builtin_convertvector(v, bf16x2_t); return __builtin_bit_cast(unsigned, b); }
; __device__ __forceinline__ void tr_all(const float* const* in, unsigned char* ws, LAS float* scr, int gw, int ngw, int lane, const TrRanges rg) {
;     ...
;         for (int i = 0; i < 16; ++i) { wp[(4 * i) * 65 + 0] = v[i][0]; wp[(4 * i) * 65 + 1] = v[i][1]; wp[(4 * i) * 65 + 2] = v[i][2]; wp[(4 * i) * 65 + 3] = v[i][3]; }
;         f32x4 g0 = {1.f, 1.f, 1.f, 1.f}, g1 = {1.f, 1.f, 1.f, 1.f};
;         if (cur.gain) { g0 = *(const f32x4*)cur.gain; g1 = *(const f32x4*)(cur.gain + 4); }
;         asm volatile("s_waitcnt lgkmcnt(0)" ::: "memory");
;         const LAS float* rp = scr + (8 * (lane & 7)) * 65 + (lane >> 3);
; #pragma unroll
;         for (int j = 0; j < 8; ++j) { const LAS float* s = rp + 8 * j;
;             u32x4 o; o.x = cvtpk(s[0 * 65] * g0[0], s[1 * 65] * g0[1]); o.y = cvtpk(s[2 * 65] * g0[2], s[3 * 65] * g0[3]);
;             o.z = cvtpk(s[4 * 65] * g1[0], s[5 * 65] * g1[1]); o.w = cvtpk(s[6 * 65] * g1[2], s[7 * 65] * g1[3]);
;             if (cur.nts) __builtin_nontemporal_store(o, (u32x4*)(cur.dst + (size_t)(8 * j) * cur.K)); else *(u32x4*)(cur.dst + (size_t)(8 * j) * cur.K) = o; }
	ds_write_b32 v70, v62 offset:15600
	ds_write_b32 v70, v63 offset:15604
	ds_write_b32 v70, v64 offset:15608
	ds_write_b32 v70, v65 offset:15612
	s_add_u32 s100, s84, 0x8f00000
	s_addc_u32 s101, s85, 0
	s_waitcnt vmcnt(0) lgkmcnt(0)
	ds_read_b32 v2, v71
	ds_read_b32 v3, v71 offset:260
	ds_read_b32 v4, v71 offset:520
	ds_read_b32 v5, v71 offset:780
	ds_read_b32 v6, v71 offset:1040
	ds_read_b32 v7, v71 offset:1300
	ds_read_b32 v8, v71 offset:1560
	ds_read_b32 v9, v71 offset:1820
	ds_read_b32 v10, v71 offset:32
	ds_read_b32 v11, v71 offset:292
	ds_read_b32 v12, v71 offset:552
	ds_read_b32 v13, v71 offset:812
	ds_read_b32 v14, v71 offset:1072
	ds_read_b32 v15, v71 offset:1332
	ds_read_b32 v16, v71 offset:1592
	ds_read_b32 v17, v71 offset:1852
	ds_read_b32 v18, v71 offset:64
	ds_read_b32 v19, v71 offset:324
	ds_read_b32 v20, v71 offset:584
	ds_read_b32 v21, v71 offset:844
	ds_read_b32 v22, v71 offset:1104
	ds_read_b32 v23, v71 offset:1364
	ds_read_b32 v24, v71 offset:1624
	ds_read_b32 v25, v71 offset:1884
	ds_read_b32 v26, v71 offset:96
	ds_read_b32 v27, v71 offset:356
	ds_read_b32 v28, v71 offset:616
	ds_read_b32 v29, v71 offset:876
	ds_read_b32 v30, v71 offset:1136
	ds_read_b32 v31, v71 offset:1396
	ds_read_b32 v32, v71 offset:1656
	ds_read_b32 v33, v71 offset:1916
	ds_read_b32 v34, v71 offset:128
	ds_read_b32 v35, v71 offset:388
	ds_read_b32 v36, v71 offset:648
	ds_read_b32 v37, v71 offset:908
	ds_read_b32 v38, v71 offset:1168
	ds_read_b32 v39, v71 offset:1428
	ds_read_b32 v40, v71 offset:1688
	ds_read_b32 v41, v71 offset:1948
	ds_read_b32 v42, v71 offset:160
	ds_read_b32 v43, v71 offset:420
	ds_read_b32 v44, v71 offset:680
	ds_read_b32 v45, v71 offset:940
	ds_read_b32 v46, v71 offset:1200
	ds_read_b32 v47, v71 offset:1460
	ds_read_b32 v48, v71 offset:1720
	ds_read_b32 v49, v71 offset:1980
	ds_read_b32 v50, v71 offset:192
	ds_read_b32 v51, v71 offset:452
	ds_read_b32 v52, v71 offset:712
	ds_read_b32 v53, v71 offset:972
	ds_read_b32 v54, v71 offset:1232
	ds_read_b32 v55, v71 offset:1492
	ds_read_b32 v56, v71 offset:1752
	ds_read_b32 v57, v71 offset:2012
	ds_read_b32 v58, v71 offset:224
	ds_read_b32 v59, v71 offset:484
	ds_read_b32 v60, v71 offset:744
	ds_read_b32 v61, v71 offset:1004
	ds_read_b32 v62, v71 offset:1264
	ds_read_b32 v63, v71 offset:1524
	ds_read_b32 v64, v71 offset:1784
	ds_read_b32 v65, v71 offset:2044
	s_waitcnt lgkmcnt(15)
	v_mul_f32_e32 v2, v2, v74
	v_mul_f32_e32 v3, v3, v75
	v_mul_f32_e32 v4, v4, v76
	v_mul_f32_e32 v5, v5, v77
	v_mul_f32_e32 v6, v6, v78
	v_mul_f32_e32 v7, v7, v79
	v_mul_f32_e32 v8, v8, v80
	v_mul_f32_e32 v9, v9, v81
	v_cvt_pk_bf16_f32 v192, v2, v3
	v_cvt_pk_bf16_f32 v193, v4, v5
	v_cvt_pk_bf16_f32 v194, v6, v7
	v_cvt_pk_bf16_f32 v195, v8, v9
	global_store_dwordx4 v72, v[192:195], s[100:101] nt
	s_waitcnt lgkmcnt(15)
	v_mul_f32_e32 v10, v10, v74
	v_mul_f32_e32 v11, v11, v75
	v_mul_f32_e32 v12, v12, v76
	v_mul_f32_e32 v13, v13, v77
	v_mul_f32_e32 v14, v14, v78
	v_mul_f32_e32 v15, v15, v79
	v_mul_f32_e32 v16, v16, v80
	v_mul_f32_e32 v17, v17, v81
	v_cvt_pk_bf16_f32 v196, v10, v11
	v_cvt_pk_bf16_f32 v197, v12, v13
	v_cvt_pk_bf16_f32 v198, v14, v15
	v_cvt_pk_bf16_f32 v199, v16, v17
	v_add_u32_e32 v68, 0x8000, v72
	global_store_dwordx4 v68, v[196:199], s[100:101] nt
	s_waitcnt lgkmcnt(15)
	v_mul_f32_e32 v18, v18, v74
	v_mul_f32_e32 v19, v19, v75
	v_mul_f32_e32 v20, v20, v76
	v_mul_f32_e32 v21, v21, v77
	v_mul_f32_e32 v22, v22, v78
	v_mul_f32_e32 v23, v23, v79
	v_mul_f32_e32 v24, v24, v80
	v_mul_f32_e32 v25, v25, v81
	v_cvt_pk_bf16_f32 v200, v18, v19
	v_cvt_pk_bf16_f32 v201, v20, v21
	v_cvt_pk_bf16_f32 v202, v22, v23
	v_cvt_pk_bf16_f32 v203, v24, v25
	v_add_u32_e32 v67, 0x10000, v72
	global_store_dwordx4 v67, v[200:203], s[100:101] nt
	s_waitcnt lgkmcnt(15)
	v_mul_f32_e32 v26, v26, v74
	v_mul_f32_e32 v27, v27, v75
	v_mul_f32_e32 v28, v28, v76
	v_mul_f32_e32 v29, v29, v77
	v_mul_f32_e32 v30, v30, v78
	v_mul_f32_e32 v31, v31, v79
	v_mul_f32_e32 v32, v32, v80
	v_mul_f32_e32 v33, v33, v81
	v_cvt_pk_bf16_f32 v204, v26, v27
	v_cvt_pk_bf16_f32 v205, v28, v29
	v_cvt_pk_bf16_f32 v206, v30, v31
	v_cvt_pk_bf16_f32 v207, v32, v33
	v_add_u32_e32 v68, 0x18000, v72
	global_store_dwordx4 v68, v[204:207], s[100:101] nt
	s_waitcnt lgkmcnt(15)
	v_mul_f32_e32 v34, v34, v74
	v_mul_f32_e32 v35, v35, v75
	v_mul_f32_e32 v36, v36, v76
	v_mul_f32_e32 v37, v37, v77
	v_mul_f32_e32 v38, v38, v78
	v_mul_f32_e32 v39, v39, v79
	v_mul_f32_e32 v40, v40, v80
	v_mul_f32_e32 v41, v41, v81
	v_cvt_pk_bf16_f32 v208, v34, v35
	v_cvt_pk_bf16_f32 v209, v36, v37
	v_cvt_pk_bf16_f32 v210, v38, v39
	v_cvt_pk_bf16_f32 v211, v40, v41
	v_add_u32_e32 v67, 0x20000, v72
	global_store_dwordx4 v67, v[208:211], s[100:101] nt
	s_waitcnt lgkmcnt(15)
	v_mul_f32_e32 v42, v42, v74
	v_mul_f32_e32 v43, v43, v75
	v_mul_f32_e32 v44, v44, v76
	v_mul_f32_e32 v45, v45, v77
	v_mul_f32_e32 v46, v46, v78
	v_mul_f32_e32 v47, v47, v79
	v_mul_f32_e32 v48, v48, v80
	v_mul_f32_e32 v49, v49, v81
	v_cvt_pk_bf16_f32 v212, v42, v43
	v_cvt_pk_bf16_f32 v213, v44, v45
	v_cvt_pk_bf16_f32 v214, v46, v47
	v_cvt_pk_bf16_f32 v215, v48, v49
	v_add_u32_e32 v68, 0x28000, v72
	global_store_dwordx4 v68, v[212:215], s[100:101] nt
	s_waitcnt lgkmcnt(8)
	v_mul_f32_e32 v50, v50, v74
	v_mul_f32_e32 v51, v51, v75
	v_mul_f32_e32 v52, v52, v76
	v_mul_f32_e32 v53, v53, v77
	v_mul_f32_e32 v54, v54, v78
	v_mul_f32_e32 v55, v55, v79
	v_mul_f32_e32 v56, v56, v80
	v_mul_f32_e32 v57, v57, v81
	v_cvt_pk_bf16_f32 v216, v50, v51
	v_cvt_pk_bf16_f32 v217, v52, v53
	v_cvt_pk_bf16_f32 v218, v54, v55
	v_cvt_pk_bf16_f32 v219, v56, v57
	v_add_u32_e32 v67, 0x30000, v72
	global_store_dwordx4 v67, v[216:219], s[100:101] nt
	s_waitcnt lgkmcnt(0)
	v_mul_f32_e32 v58, v58, v74
	v_mul_f32_e32 v59, v59, v75
	v_mul_f32_e32 v60, v60, v76
	v_mul_f32_e32 v61, v61, v77
	v_mul_f32_e32 v62, v62, v78
	v_mul_f32_e32 v63, v63, v79
	v_mul_f32_e32 v64, v64, v80
	v_mul_f32_e32 v65, v65, v81
	v_cvt_pk_bf16_f32 v220, v58, v59
	v_cvt_pk_bf16_f32 v221, v60, v61
	v_cvt_pk_bf16_f32 v222, v62, v63
	v_cvt_pk_bf16_f32 v223, v64, v65
	v_add_u32_e32 v68, 0x38000, v72
	global_store_dwordx4 v68, v[220:223], s[100:101] nt

; #define LAS __attribute__((address_space(3)))
; #define TR_LOAD(p) __builtin_nontemporal_load(p)
; __device__ __forceinline__ TrItem tr_decode(int it, const float* const* in, unsigned char* ws, int lane) {
;     ...
;     const int rh = r >> 3, rl = r & 7, nq = ndb >> DL, kbh = rh / nq, dbh = rh - kbh * nq;
;     const int kb = (kbh << KL) + (rl >> DL), db = (dbh << DL) + (rl & ((1 << DL) - 1)), d0 = db * 64, k0 = kb * 64;
;     ...
;     const int kb = r / ndb, db = r - kb * ndb, d0 = db * 64, k0 = kb * 64;
;     ...
;     const int blk = d0 + 32 * ((lane & 15) >> 3);
;     const float* src = W; int s0 = blk;
;     if (kind == 1) { const int pn = blk >> 8, bj = (blk >> 7) & 1, o = blk & 127; src = bj ? W2 : W; s0 = pn * 128 + o; }
;     else if (kind == 2) s0 = win_src(blk);
;     TrItem t; t.src = src + (size_t)(k0 + (lane >> 4)) * N + s0 + 4 * (lane & 7); t.gain = gain ? gain + k0 + 8 * (lane & 7) : nullptr;
;     t.dst = WT + (size_t)(d0 + (lane >> 3)) * K + k0 + 8 * (lane & 7); t.N = N; t.K = K; t.nts = nts && TR_NTS;
; __device__ __forceinline__ void tr_all(const float* const* in, unsigned char* ws, LAS float* scr, int gw, int ngw, int lane, const TrRanges rg) {
;     ...
;     for (int i = 0; i < 16; ++i) v[i] = TR_LOAD((const f32x4*)(cur.src + (size_t)(4 * i) * cur.N));
;     for (int it = gw; it < TR_CNT; it += ngw) {
;         const int nit = it + ngw; const bool hn = nit < TR_CNT;
;         TrItem nx = cur; f32x4 w[16];
;         if (hn) { nx = tr_decode(rg.item(nit), in, ws, lane);
; #pragma unroll
;             for (int i = 0; i < 16; ++i) w[i] = TR_LOAD((const f32x4*)(nx.src + (size_t)(4 * i) * nx.N)); }
;         LAS float* wp = scr + (lane >> 4) * 65 + 4 * (lane & 15);
; #pragma unroll
;         for (int i = 0; i < 16; ++i) { wp[(4 * i) * 65 + 0] = v[i][0]; wp[(4 * i) * 65 + 1] = v[i][1]; wp[(4 * i) * 65 + 2] = v[i][2]; wp[(4 * i) * 65 + 3] = v[i][3]; }
.Lseam_cv_1:
	s_cmp_lt_u32 s98, 2
	s_cbranch_scc1 .LBB0_570
	s_cmp_gt_u32 s98, 5
	s_cbranch_scc1 .LBB0_570
	s_mov_b64 exec, -1
	s_lshl_b32 s99, s87, 2
	s_add_i32 s99, s99, s98
	s_add_i32 s99, s99, 0x9fe
	s_lshr_b32 s100, s99, 3
	s_mul_i32 s101, s100, 0x5d2
	s_lshr_b32 s101, s101, 16
	s_mul_i32 vcc_lo, s101, 44
	s_sub_i32 s100, s100, vcc_lo
	s_and_b32 vcc_lo, s99, 7
	s_lshr_b32 vcc_hi, vcc_lo, 2
	s_lshl_b32 s101, s101, 1
	s_add_i32 s101, s101, vcc_hi
	s_and_b32 vcc_lo, vcc_lo, 3
	s_lshl_b32 s100, s100, 2
	s_add_i32 s100, s100, vcc_lo
	s_lshl_b32 s101, s101, 6
	s_lshl_b32 s100, s100, 6
	v_and_b32_e32 v66, 63, v1
	v_lshrrev_b32_e32 v67, 4, v66
	v_and_b32_e32 v68, 15, v66
	v_and_b32_e32 v73, 7, v66
	v_lshrrev_b32_e32 v72, 3, v66
	s_mul_i32 s99, s98, 0x4100
	v_mul_u32_u24_e32 v70, 0x104, v67
	v_lshl_add_u32 v70, v68, 4, v70
	v_add_u32_e32 v70, s99, v70
	v_mul_u32_u24_e32 v71, 0x820, v73
	v_lshl_add_u32 v71, v72, 2, v71
	v_add_u32_e32 v71, s99, v71
	s_mul_i32 s99, s101, 0x1600
	s_lshr_b32 vcc_lo, s100, 8
	s_lshl_b32 vcc_lo, vcc_lo, 7
	s_add_i32 s99, s99, vcc_lo
	s_and_b32 vcc_lo, s100, 0x7f
	s_add_i32 s99, s99, vcc_lo
	s_lshl_b32 s99, s99, 2
	v_mul_u32_u24_e32 v69, 0x5800, v67
	v_lshl_add_u32 v69, v68, 4, v69
	v_add_u32_e32 v69, s99, v69
	s_lshl_b32 s99, s100, 12
	s_lshl_b32 vcc_lo, s101, 1
	s_add_i32 s99, s99, vcc_lo
	v_lshlrev_b32_e32 v72, 12, v72
	v_lshl_add_u32 v72, v73, 4, v72
	v_add_u32_e32 v72, s99, v72
	s_lshl_b32 s99, s101, 2
	v_lshlrev_b32_e32 v73, 5, v73
	v_add_u32_e32 v73, s99, v73
	s_nop 0
	s_bitcmp1_b32 s100, 7
	v_readlane_b32 s100, v254, 6
	v_readlane_b32 s101, v254, 7
	v_readlane_b32 s98, v254, 8
	v_readlane_b32 s99, v254, 9
	s_nop 3
	s_cselect_b32 s100, s98, s100
	s_cselect_b32 s101, s99, s101
	v_readlane_b32 s98, v254, 4
	v_readlane_b32 s99, v254, 5
	global_load_dwordx4 v[2:5], v69, s[100:101] nt
	v_add_u32_e32 v68, 0x16000, v69
	global_load_dwordx4 v[6:9], v68, s[100:101] nt
	v_add_u32_e32 v67, 0x2c000, v69
	global_load_dwordx4 v[10:13], v67, s[100:101] nt
	v_add_u32_e32 v68, 0x42000, v69
	global_load_dwordx4 v[14:17], v68, s[100:101] nt
	v_add_u32_e32 v67, 0x58000, v69
	global_load_dwordx4 v[18:21], v67, s[100:101] nt
	v_add_u32_e32 v68, 0x6e000, v69
	global_load_dwordx4 v[22:25], v68, s[100:101] nt
	v_add_u32_e32 v67, 0x84000, v69
	global_load_dwordx4 v[26:29], v67, s[100:101] nt
	v_add_u32_e32 v68, 0x9a000, v69
	global_load_dwordx4 v[30:33], v68, s[100:101] nt
	v_add_u32_e32 v67, 0xb0000, v69
	global_load_dwordx4 v[34:37], v67, s[100:101] nt
	v_add_u32_e32 v68, 0xc6000, v69
	global_load_dwordx4 v[38:41], v68, s[100:101] nt
	v_add_u32_e32 v67, 0xdc000, v69
	global_load_dwordx4 v[42:45], v67, s[100:101] nt
	v_add_u32_e32 v68, 0xf2000, v69
	global_load_dwordx4 v[46:49], v68, s[100:101] nt
	v_add_u32_e32 v67, 0x108000, v69
	global_load_dwordx4 v[50:53], v67, s[100:101] nt
	v_add_u32_e32 v68, 0x11e000, v69
	global_load_dwordx4 v[54:57], v68, s[100:101] nt
	v_add_u32_e32 v67, 0x134000, v69
	global_load_dwordx4 v[58:61], v67, s[100:101] nt
	v_add_u32_e32 v68, 0x14a000, v69
	global_load_dwordx4 v[62:65], v68, s[100:101] nt
	global_load_dwordx4 v[74:77], v73, s[98:99]
	global_load_dwordx4 v[78:81], v73, s[98:99] offset:16
	s_waitcnt vmcnt(17)
	ds_write_b32 v70, v2
	ds_write_b32 v70, v3 offset:4
	ds_write_b32 v70, v4 offset:8
	ds_write_b32 v70, v5 offset:12
	s_waitcnt vmcnt(16)
	ds_write_b32 v70, v6 offset:1040
	ds_write_b32 v70, v7 offset:1044
	ds_write_b32 v70, v8 offset:1048
	ds_write_b32 v70, v9 offset:1052
	s_waitcnt vmcnt(15)
	ds_write_b32 v70, v10 offset:2080
	ds_write_b32 v70, v11 offset:2084
	ds_write_b32 v70, v12 offset:2088
	ds_write_b32 v70, v13 offset:2092
	s_waitcnt vmcnt(14)
	ds_write_b32 v70, v14 offset:3120
	ds_write_b32 v70, v15 offset:3124
	ds_write_b32 v70, v16 offset:3128
	ds_write_b32 v70, v17 offset:3132
	s_waitcnt vmcnt(13)
	ds_write_b32 v70, v18 offset:4160
	ds_write_b32 v70, v19 offset:4164
	ds_write_b32 v70, v20 offset:4168
	ds_write_b32 v70, v21 offset:4172
	s_waitcnt vmcnt(12)
	ds_write_b32 v70, v22 offset:5200
	ds_write_b32 v70, v23 offset:5204
	ds_write_b32 v70, v24 offset:5208
	ds_write_b32 v70, v25 offset:5212
	s_waitcnt vmcnt(11)
	ds_write_b32 v70, v26 offset:6240
	ds_write_b32 v70, v27 offset:6244
	ds_write_b32 v70, v28 offset:6248
	ds_write_b32 v70, v29 offset:6252
	s_waitcnt vmcnt(10)
	ds_write_b32 v70, v30 offset:7280
	ds_write_b32 v70, v31 offset:7284
	ds_write_b32 v70, v32 offset:7288
	ds_write_b32 v70, v33 offset:7292
	s_waitcnt vmcnt(9)
	ds_write_b32 v70, v34 offset:8320
	ds_write_b32 v70, v35 offset:8324
	ds_write_b32 v70, v36 offset:8328
	ds_write_b32 v70, v37 offset:8332
	s_waitcnt vmcnt(8)
	ds_write_b32 v70, v38 offset:9360
	ds_write_b32 v70, v39 offset:9364
	ds_write_b32 v70, v40 offset:9368
	ds_write_b32 v70, v41 offset:9372
	s_waitcnt vmcnt(7)
	ds_write_b32 v70, v42 offset:10400
	ds_write_b32 v70, v43 offset:10404
	ds_write_b32 v70, v44 offset:10408
	ds_write_b32 v70, v45 offset:10412
	s_waitcnt vmcnt(6)
	ds_write_b32 v70, v46 offset:11440
	ds_write_b32 v70, v47 offset:11444
	ds_write_b32 v70, v48 offset:11448
	ds_write_b32 v70, v49 offset:11452
	s_waitcnt vmcnt(5)
	ds_write_b32 v70, v50 offset:12480
	ds_write_b32 v70, v51 offset:12484
	ds_write_b32 v70, v52 offset:12488
	ds_write_b32 v70, v53 offset:12492
	s_waitcnt vmcnt(4)
	ds_write_b32 v70, v54 offset:13520
	ds_write_b32 v70, v55 offset:13524
	ds_write_b32 v70, v56 offset:13528
	ds_write_b32 v70, v57 offset:13532
	s_waitcnt vmcnt(3)
	ds_write_b32 v70, v58 offset:14560
	ds_write_b32 v70, v59 offset:14564
	ds_write_b32 v70, v60 offset:14568
	ds_write_b32 v70, v61 offset:14572
	s_waitcnt vmcnt(2)
; #define LAS __attribute__((address_space(3)))
; __device__ __forceinline__ unsigned cvtpk(float lo, float hi) { f32x2_t v = {lo, hi}; bf16x2_t b = __builtin_convertvector(v, bf16x2_t); return __builtin_bit_cast(unsigned, b); }
; __device__ __forceinline__ void tr_all(const float* const* in, unsigned char* ws, LAS float* scr, int gw, int ngw, int lane, const TrRanges rg) {
;     ...
;         for (int i = 0; i < 16; ++i) { wp[(4 * i) * 65 + 0] = v[i][0]; wp[(4 * i) * 65 + 1] = v[i][1]; wp[(4 * i) * 65 + 2] = v[i][2]; wp[(4 * i) * 65 + 3] = v[i][3]; }
;         f32x4 g0 = {1.f, 1.f, 1.f, 1.f}, g1 = {1.f, 1.f, 1.f, 1.f};
;         if (cur.gain) { g0 = *(const f32x4*)cur.gain; g1 = *(const f32x4*)(cur.gain + 4); }
;         asm volatile("s_waitcnt lgkmcnt(0)" ::: "memory");
;         const LAS float* rp = scr + (8 * (lane & 7)) * 65 + (lane >> 3);
; #pragma unroll
;         for (int j = 0; j < 8; ++j) { const LAS float* s = rp + 8 * j;
;             u32x4 o; o.x = cvtpk(s[0 * 65] * g0[0], s[1 * 65] * g0[1]); o.y = cvtpk(s[2 * 65] * g0[2], s[3 * 65] * g0[3]);
;             o.z = cvtpk(s[4 * 65] * g1[0], s[5 * 65] * g1[1]); o.w = cvtpk(s[6 * 65] * g1[2], s[7 * 65] * g1[3]);
;             if (cur.nts) __builtin_nontemporal_store(o, (u32x4*)(cur.dst + (size_t)(8 * j) * cur.K)); else *(u32x4*)(cur.dst + (size_t)(8 * j) * cur.K) = o; }
	ds_write_b32 v70, v62 offset:15600
	ds_write_b32 v70, v63 offset:15604
	ds_write_b32 v70, v64 offset:15608
	ds_write_b32 v70, v65 offset:15612
	s_add_u32 s100, s84, 0x8f00000
	s_addc_u32 s101, s85, 0
	s_waitcnt vmcnt(0) lgkmcnt(0)
	ds_read_b32 v2, v71
	ds_read_b32 v3, v71 offset:260
	ds_read_b32 v4, v71 offset:520
	ds_read_b32 v5, v71 offset:780
	ds_read_b32 v6, v71 offset:1040
	ds_read_b32 v7, v71 offset:1300
	ds_read_b32 v8, v71 offset:1560
	ds_read_b32 v9, v71 offset:1820
	ds_read_b32 v10, v71 offset:32
	ds_read_b32 v11, v71 offset:292
	ds_read_b32 v12, v71 offset:552
	ds_read_b32 v13, v71 offset:812
	ds_read_b32 v14, v71 offset:1072
	ds_read_b32 v15, v71 offset:1332
	ds_read_b32 v16, v71 offset:1592
	ds_read_b32 v17, v71 offset:1852
	ds_read_b32 v18, v71 offset:64
	ds_read_b32 v19, v71 offset:324
	ds_read_b32 v20, v71 offset:584
	ds_read_b32 v21, v71 offset:844
	ds_read_b32 v22, v71 offset:1104
	ds_read_b32 v23, v71 offset:1364
	ds_read_b32 v24, v71 offset:1624
	ds_read_b32 v25, v71 offset:1884
	ds_read_b32 v26, v71 offset:96
	ds_read_b32 v27, v71 offset:356
	ds_read_b32 v28, v71 offset:616
	ds_read_b32 v29, v71 offset:876
	ds_read_b32 v30, v71 offset:1136
	ds_read_b32 v31, v71 offset:1396
	ds_read_b32 v32, v71 offset:1656
	ds_read_b32 v33, v71 offset:1916
	ds_read_b32 v34, v71 offset:128
	ds_read_b32 v35, v71 offset:388
	ds_read_b32 v36, v71 offset:648
	ds_read_b32 v37, v71 offset:908
	ds_read_b32 v38, v71 offset:1168
	ds_read_b32 v39, v71 offset:1428
	ds_read_b32 v40, v71 offset:1688
	ds_read_b32 v41, v71 offset:1948
	ds_read_b32 v42, v71 offset:160
	ds_read_b32 v43, v71 offset:420
	ds_read_b32 v44, v71 offset:680
	ds_read_b32 v45, v71 offset:940
	ds_read_b32 v46, v71 offset:1200
	ds_read_b32 v47, v71 offset:1460
	ds_read_b32 v48, v71 offset:1720
	ds_read_b32 v49, v71 offset:1980
	ds_read_b32 v50, v71 offset:192
	ds_read_b32 v51, v71 offset:452
	ds_read_b32 v52, v71 offset:712
	ds_read_b32 v53, v71 offset:972
	ds_read_b32 v54, v71 offset:1232
	ds_read_b32 v55, v71 offset:1492
	ds_read_b32 v56, v71 offset:1752
	ds_read_b32 v57, v71 offset:2012
	ds_read_b32 v58, v71 offset:224
	ds_read_b32 v59, v71 offset:484
	ds_read_b32 v60, v71 offset:744
	ds_read_b32 v61, v71 offset:1004
	ds_read_b32 v62, v71 offset:1264
	ds_read_b32 v63, v71 offset:1524
	ds_read_b32 v64, v71 offset:1784
	ds_read_b32 v65, v71 offset:2044
	s_waitcnt lgkmcnt(15)
	v_mul_f32_e32 v2, v2, v74
	v_mul_f32_e32 v3, v3, v75
	v_mul_f32_e32 v4, v4, v76
	v_mul_f32_e32 v5, v5, v77
	v_mul_f32_e32 v6, v6, v78
	v_mul_f32_e32 v7, v7, v79
	v_mul_f32_e32 v8, v8, v80
	v_mul_f32_e32 v9, v9, v81
	v_cvt_pk_bf16_f32 v192, v2, v3
	v_cvt_pk_bf16_f32 v193, v4, v5
	v_cvt_pk_bf16_f32 v194, v6, v7
	v_cvt_pk_bf16_f32 v195, v8, v9
	global_store_dwordx4 v72, v[192:195], s[100:101] nt
	s_waitcnt lgkmcnt(15)
	v_mul_f32_e32 v10, v10, v74
	v_mul_f32_e32 v11, v11, v75
	v_mul_f32_e32 v12, v12, v76
	v_mul_f32_e32 v13, v13, v77
	v_mul_f32_e32 v14, v14, v78
	v_mul_f32_e32 v15, v15, v79
	v_mul_f32_e32 v16, v16, v80
	v_mul_f32_e32 v17, v17, v81
	v_cvt_pk_bf16_f32 v196, v10, v11
	v_cvt_pk_bf16_f32 v197, v12, v13
	v_cvt_pk_bf16_f32 v198, v14, v15
	v_cvt_pk_bf16_f32 v199, v16, v17
	v_add_u32_e32 v68, 0x8000, v72
	global_store_dwordx4 v68, v[196:199], s[100:101] nt
	s_waitcnt lgkmcnt(15)
	v_mul_f32_e32 v18, v18, v74
	v_mul_f32_e32 v19, v19, v75
	v_mul_f32_e32 v20, v20, v76
	v_mul_f32_e32 v21, v21, v77
	v_mul_f32_e32 v22, v22, v78
	v_mul_f32_e32 v23, v23, v79
	v_mul_f32_e32 v24, v24, v80
	v_mul_f32_e32 v25, v25, v81
	v_cvt_pk_bf16_f32 v200, v18, v19
	v_cvt_pk_bf16_f32 v201, v20, v21
	v_cvt_pk_bf16_f32 v202, v22, v23
	v_cvt_pk_bf16_f32 v203, v24, v25
	v_add_u32_e32 v67, 0x10000, v72
	global_store_dwordx4 v67, v[200:203], s[100:101] nt
	s_waitcnt lgkmcnt(15)
	v_mul_f32_e32 v26, v26, v74
	v_mul_f32_e32 v27, v27, v75
	v_mul_f32_e32 v28, v28, v76
	v_mul_f32_e32 v29, v29, v77
	v_mul_f32_e32 v30, v30, v78
	v_mul_f32_e32 v31, v31, v79
	v_mul_f32_e32 v32, v32, v80
	v_mul_f32_e32 v33, v33, v81
	v_cvt_pk_bf16_f32 v204, v26, v27
	v_cvt_pk_bf16_f32 v205, v28, v29
	v_cvt_pk_bf16_f32 v206, v30, v31
	v_cvt_pk_bf16_f32 v207, v32, v33
	v_add_u32_e32 v68, 0x18000, v72
	global_store_dwordx4 v68, v[204:207], s[100:101] nt
	s_waitcnt lgkmcnt(15)
	v_mul_f32_e32 v34, v34, v74
	v_mul_f32_e32 v35, v35, v75
	v_mul_f32_e32 v36, v36, v76
	v_mul_f32_e32 v37, v37, v77
	v_mul_f32_e32 v38, v38, v78
	v_mul_f32_e32 v39, v39, v79
	v_mul_f32_e32 v40, v40, v80
	v_mul_f32_e32 v41, v41, v81
	v_cvt_pk_bf16_f32 v208, v34, v35
	v_cvt_pk_bf16_f32 v209, v36, v37
	v_cvt_pk_bf16_f32 v210, v38, v39
	v_cvt_pk_bf16_f32 v211, v40, v41
	v_add_u32_e32 v67, 0x20000, v72
	global_store_dwordx4 v67, v[208:211], s[100:101] nt
	s_waitcnt lgkmcnt(15)
	v_mul_f32_e32 v42, v42, v74
	v_mul_f32_e32 v43, v43, v75
	v_mul_f32_e32 v44, v44, v76
	v_mul_f32_e32 v45, v45, v77
	v_mul_f32_e32 v46, v46, v78
	v_mul_f32_e32 v47, v47, v79
	v_mul_f32_e32 v48, v48, v80
	v_mul_f32_e32 v49, v49, v81
	v_cvt_pk_bf16_f32 v212, v42, v43
	v_cvt_pk_bf16_f32 v213, v44, v45
	v_cvt_pk_bf16_f32 v214, v46, v47
	v_cvt_pk_bf16_f32 v215, v48, v49
	v_add_u32_e32 v68, 0x28000, v72
	global_store_dwordx4 v68, v[212:215], s[100:101] nt
	s_waitcnt lgkmcnt(8)
	v_mul_f32_e32 v50, v50, v74
	v_mul_f32_e32 v51, v51, v75
	v_mul_f32_e32 v52, v52, v76
	v_mul_f32_e32 v53, v53, v77
	v_mul_f32_e32 v54, v54, v78
	v_mul_f32_e32 v55, v55, v79
	v_mul_f32_e32 v56, v56, v80
	v_mul_f32_e32 v57, v57, v81
	v_cvt_pk_bf16_f32 v216, v50, v51
	v_cvt_pk_bf16_f32 v217, v52, v53
	v_cvt_pk_bf16_f32 v218, v54, v55
	v_cvt_pk_bf16_f32 v219, v56, v57
	v_add_u32_e32 v67, 0x30000, v72
	global_store_dwordx4 v67, v[216:219], s[100:101] nt
	s_waitcnt lgkmcnt(0)
	v_mul_f32_e32 v58, v58, v74
	v_mul_f32_e32 v59, v59, v75
	v_mul_f32_e32 v60, v60, v76
	v_mul_f32_e32 v61, v61, v77
	v_mul_f32_e32 v62, v62, v78
	v_mul_f32_e32 v63, v63, v79
	v_mul_f32_e32 v64, v64, v80
	v_mul_f32_e32 v65, v65, v81
	v_cvt_pk_bf16_f32 v220, v58, v59
	v_cvt_pk_bf16_f32 v221, v60, v61
	v_cvt_pk_bf16_f32 v222, v62, v63
	v_cvt_pk_bf16_f32 v223, v64, v65
	v_add_u32_e32 v68, 0x38000, v72
	global_store_dwordx4 v68, v[220:223], s[100:101] nt

; #define LAS __attribute__((address_space(3)))
; #define TR_LOAD(p) __builtin_nontemporal_load(p)
; __device__ __forceinline__ TrItem tr_decode(int it, const float* const* in, unsigned char* ws, int lane) {
;     ...
;     const int rh = r >> 3, rl = r & 7, nq = ndb >> DL, kbh = rh / nq, dbh = rh - kbh * nq;
;     const int kb = (kbh << KL) + (rl >> DL), db = (dbh << DL) + (rl & ((1 << DL) - 1)), d0 = db * 64, k0 = kb * 64;
;     ...
;     const int kb = r / ndb, db = r - kb * ndb, d0 = db * 64, k0 = kb * 64;
;     ...
;     const int blk = d0 + 32 * ((lane & 15) >> 3);
;     const float* src = W; int s0 = blk;
;     if (kind == 1) { const int pn = blk >> 8, bj = (blk >> 7) & 1, o = blk & 127; src = bj ? W2 : W; s0 = pn * 128 + o; }
;     else if (kind == 2) s0 = win_src(blk);
;     TrItem t; t.src = src + (size_t)(k0 + (lane >> 4)) * N + s0 + 4 * (lane & 7); t.gain = gain ? gain + k0 + 8 * (lane & 7) : nullptr;
;     t.dst = WT + (size_t)(d0 + (lane >> 3)) * K + k0 + 8 * (lane & 7); t.N = N; t.K = K; t.nts = nts && TR_NTS;
; __device__ __forceinline__ void tr_all(const float* const* in, unsigned char* ws, LAS float* scr, int gw, int ngw, int lane, const TrRanges rg) {
;     ...
;     for (int i = 0; i < 16; ++i) v[i] = TR_LOAD((const f32x4*)(cur.src + (size_t)(4 * i) * cur.N));
;     for (int it = gw; it < TR_CNT; it += ngw) {
;         const int nit = it + ngw; const bool hn = nit < TR_CNT;
;         TrItem nx = cur; f32x4 w[16];
;         if (hn) { nx = tr_decode(rg.item(nit), in, ws, lane);
; #pragma unroll
;             for (int i = 0; i < 16; ++i) w[i] = TR_LOAD((const f32x4*)(nx.src + (size_t)(4 * i) * nx.N)); }
;         LAS float* wp = scr + (lane >> 4) * 65 + 4 * (lane & 15);
; #pragma unroll
;         for (int i = 0; i < 16; ++i) { wp[(4 * i) * 65 + 0] = v[i][0]; wp[(4 * i) * 65 + 1] = v[i][1]; wp[(4 * i) * 65 + 2] = v[i][2]; wp[(4 * i) * 65 + 3] = v[i][3]; }
.Lseam_cv_2:
	s_cmp_lt_u32 s98, 2
	s_cbranch_scc1 .LBB0_681
	s_cmp_gt_u32 s98, 5
	s_cbranch_scc1 .LBB0_681
	s_mov_b64 exec, -1
	s_lshl_b32 s99, s87, 2
	s_add_i32 s99, s99, s98
	s_add_i32 s99, s99, 0xdfe
	s_lshr_b32 s100, s99, 3
	s_mul_i32 s101, s100, 0x5d2
	s_lshr_b32 s101, s101, 16
	s_mul_i32 vcc_lo, s101, 44
	s_sub_i32 s100, s100, vcc_lo
	s_and_b32 vcc_lo, s99, 7
	s_lshr_b32 vcc_hi, vcc_lo, 2
	s_lshl_b32 s101, s101, 1
	s_add_i32 s101, s101, vcc_hi
	s_and_b32 vcc_lo, vcc_lo, 3
	s_lshl_b32 s100, s100, 2
	s_add_i32 s100, s100, vcc_lo
	s_lshl_b32 s101, s101, 6
	s_lshl_b32 s100, s100, 6
	v_and_b32_e32 v66, 63, v1
	v_lshrrev_b32_e32 v67, 4, v66
	v_and_b32_e32 v68, 15, v66
	v_and_b32_e32 v73, 7, v66
	v_lshrrev_b32_e32 v72, 3, v66
	s_mul_i32 s99, s98, 0x4100
	v_mul_u32_u24_e32 v70, 0x104, v67
	v_lshl_add_u32 v70, v68, 4, v70
	v_add_u32_e32 v70, s99, v70
	v_mul_u32_u24_e32 v71, 0x820, v73
	v_lshl_add_u32 v71, v72, 2, v71
	v_add_u32_e32 v71, s99, v71
	s_mul_i32 s99, s101, 0x1600
	s_lshr_b32 vcc_lo, s100, 8
	s_lshl_b32 vcc_lo, vcc_lo, 7
	s_add_i32 s99, s99, vcc_lo
	s_and_b32 vcc_lo, s100, 0x7f
	s_add_i32 s99, s99, vcc_lo
	s_lshl_b32 s99, s99, 2
	v_mul_u32_u24_e32 v69, 0x5800, v67
	v_lshl_add_u32 v69, v68, 4, v69
	v_add_u32_e32 v69, s99, v69
	s_lshl_b32 s99, s100, 12
	s_lshl_b32 vcc_lo, s101, 1
	s_add_i32 s99, s99, vcc_lo
	v_lshlrev_b32_e32 v72, 12, v72
	v_lshl_add_u32 v72, v73, 4, v72
	v_add_u32_e32 v72, s99, v72
	s_lshl_b32 s99, s101, 2
	v_lshlrev_b32_e32 v73, 5, v73
	v_add_u32_e32 v73, s99, v73
	s_nop 0
	s_bitcmp1_b32 s100, 7
	v_readlane_b32 s100, v254, 6
	v_readlane_b32 s101, v254, 7
	v_readlane_b32 s98, v254, 8
	v_readlane_b32 s99, v254, 9
	s_nop 3
	s_cselect_b32 s100, s98, s100
	s_cselect_b32 s101, s99, s101
	v_readlane_b32 s98, v254, 4
	v_readlane_b32 s99, v254, 5
	global_load_dwordx4 v[2:5], v69, s[100:101] nt
	v_add_u32_e32 v68, 0x16000, v69
	global_load_dwordx4 v[6:9], v68, s[100:101] nt
	v_add_u32_e32 v67, 0x2c000, v69
	global_load_dwordx4 v[10:13], v67, s[100:101] nt
	v_add_u32_e32 v68, 0x42000, v69
	global_load_dwordx4 v[14:17], v68, s[100:101] nt
	v_add_u32_e32 v67, 0x58000, v69
	global_load_dwordx4 v[18:21], v67, s[100:101] nt
	v_add_u32_e32 v68, 0x6e000, v69
	global_load_dwordx4 v[22:25], v68, s[100:101] nt
	v_add_u32_e32 v67, 0x84000, v69
	global_load_dwordx4 v[26:29], v67, s[100:101] nt
	v_add_u32_e32 v68, 0x9a000, v69
	global_load_dwordx4 v[30:33], v68, s[100:101] nt
	v_add_u32_e32 v67, 0xb0000, v69
	global_load_dwordx4 v[34:37], v67, s[100:101] nt
	v_add_u32_e32 v68, 0xc6000, v69
	global_load_dwordx4 v[38:41], v68, s[100:101] nt
	v_add_u32_e32 v67, 0xdc000, v69
	global_load_dwordx4 v[42:45], v67, s[100:101] nt
	v_add_u32_e32 v68, 0xf2000, v69
	global_load_dwordx4 v[46:49], v68, s[100:101] nt
	v_add_u32_e32 v67, 0x108000, v69
	global_load_dwordx4 v[50:53], v67, s[100:101] nt
	v_add_u32_e32 v68, 0x11e000, v69
	global_load_dwordx4 v[54:57], v68, s[100:101] nt
	v_add_u32_e32 v67, 0x134000, v69
	global_load_dwordx4 v[58:61], v67, s[100:101] nt
	v_add_u32_e32 v68, 0x14a000, v69
	global_load_dwordx4 v[62:65], v68, s[100:101] nt
	global_load_dwordx4 v[74:77], v73, s[98:99]
	global_load_dwordx4 v[78:81], v73, s[98:99] offset:16
	s_waitcnt vmcnt(17)
	ds_write_b32 v70, v2
	ds_write_b32 v70, v3 offset:4
	ds_write_b32 v70, v4 offset:8
	ds_write_b32 v70, v5 offset:12
	s_waitcnt vmcnt(16)
	ds_write_b32 v70, v6 offset:1040
	ds_write_b32 v70, v7 offset:1044
	ds_write_b32 v70, v8 offset:1048
	ds_write_b32 v70, v9 offset:1052
	s_waitcnt vmcnt(15)
	ds_write_b32 v70, v10 offset:2080
	ds_write_b32 v70, v11 offset:2084
	ds_write_b32 v70, v12 offset:2088
	ds_write_b32 v70, v13 offset:2092
	s_waitcnt vmcnt(14)
	ds_write_b32 v70, v14 offset:3120
	ds_write_b32 v70, v15 offset:3124
	ds_write_b32 v70, v16 offset:3128
	ds_write_b32 v70, v17 offset:3132
	s_waitcnt vmcnt(13)
	ds_write_b32 v70, v18 offset:4160
	ds_write_b32 v70, v19 offset:4164
	ds_write_b32 v70, v20 offset:4168
	ds_write_b32 v70, v21 offset:4172
	s_waitcnt vmcnt(12)
	ds_write_b32 v70, v22 offset:5200
	ds_write_b32 v70, v23 offset:5204
	ds_write_b32 v70, v24 offset:5208
	ds_write_b32 v70, v25 offset:5212
	s_waitcnt vmcnt(11)
	ds_write_b32 v70, v26 offset:6240
	ds_write_b32 v70, v27 offset:6244
	ds_write_b32 v70, v28 offset:6248
	ds_write_b32 v70, v29 offset:6252
	s_waitcnt vmcnt(10)
	ds_write_b32 v70, v30 offset:7280
	ds_write_b32 v70, v31 offset:7284
	ds_write_b32 v70, v32 offset:7288
	ds_write_b32 v70, v33 offset:7292
	s_waitcnt vmcnt(9)
	ds_write_b32 v70, v34 offset:8320
	ds_write_b32 v70, v35 offset:8324
	ds_write_b32 v70, v36 offset:8328
	ds_write_b32 v70, v37 offset:8332
	s_waitcnt vmcnt(8)
	ds_write_b32 v70, v38 offset:9360
	ds_write_b32 v70, v39 offset:9364
	ds_write_b32 v70, v40 offset:9368
	ds_write_b32 v70, v41 offset:9372
	s_waitcnt vmcnt(7)
	ds_write_b32 v70, v42 offset:10400
	ds_write_b32 v70, v43 offset:10404
	ds_write_b32 v70, v44 offset:10408
	ds_write_b32 v70, v45 offset:10412
	s_waitcnt vmcnt(6)
	ds_write_b32 v70, v46 offset:11440
	ds_write_b32 v70, v47 offset:11444
	ds_write_b32 v70, v48 offset:11448
	ds_write_b32 v70, v49 offset:11452
	s_waitcnt vmcnt(5)
	ds_write_b32 v70, v50 offset:12480
	ds_write_b32 v70, v51 offset:12484
	ds_write_b32 v70, v52 offset:12488
	ds_write_b32 v70, v53 offset:12492
	s_waitcnt vmcnt(4)
	ds_write_b32 v70, v54 offset:13520
	ds_write_b32 v70, v55 offset:13524
	ds_write_b32 v70, v56 offset:13528
	ds_write_b32 v70, v57 offset:13532
	s_waitcnt vmcnt(3)
	ds_write_b32 v70, v58 offset:14560
	ds_write_b32 v70, v59 offset:14564
	ds_write_b32 v70, v60 offset:14568
	ds_write_b32 v70, v61 offset:14572
	s_waitcnt vmcnt(2)
; #define LAS __attribute__((address_space(3)))
; __device__ __forceinline__ unsigned cvtpk(float lo, float hi) { f32x2_t v = {lo, hi}; bf16x2_t b = __builtin_convertvector(v, bf16x2_t); return __builtin_bit_cast(unsigned, b); }
; __device__ __forceinline__ void tr_all(const float* const* in, unsigned char* ws, LAS float* scr, int gw, int ngw, int lane, const TrRanges rg) {
;     ...
;         for (int i = 0; i < 16; ++i) { wp[(4 * i) * 65 + 0] = v[i][0]; wp[(4 * i) * 65 + 1] = v[i][1]; wp[(4 * i) * 65 + 2] = v[i][2]; wp[(4 * i) * 65 + 3] = v[i][3]; }
;         f32x4 g0 = {1.f, 1.f, 1.f, 1.f}, g1 = {1.f, 1.f, 1.f, 1.f};
;         if (cur.gain) { g0 = *(const f32x4*)cur.gain; g1 = *(const f32x4*)(cur.gain + 4); }
;         asm volatile("s_waitcnt lgkmcnt(0)" ::: "memory");
;         const LAS float* rp = scr + (8 * (lane & 7)) * 65 + (lane >> 3);
; #pragma unroll
;         for (int j = 0; j < 8; ++j) { const LAS float* s = rp + 8 * j;
;             u32x4 o; o.x = cvtpk(s[0 * 65] * g0[0], s[1 * 65] * g0[1]); o.y = cvtpk(s[2 * 65] * g0[2], s[3 * 65] * g0[3]);
;             o.z = cvtpk(s[4 * 65] * g1[0], s[5 * 65] * g1[1]); o.w = cvtpk(s[6 * 65] * g1[2], s[7 * 65] * g1[3]);
;             if (cur.nts) __builtin_nontemporal_store(o, (u32x4*)(cur.dst + (size_t)(8 * j) * cur.K)); else *(u32x4*)(cur.dst + (size_t)(8 * j) * cur.K) = o; }
	ds_write_b32 v70, v62 offset:15600
	ds_write_b32 v70, v63 offset:15604
	ds_write_b32 v70, v64 offset:15608
	ds_write_b32 v70, v65 offset:15612
	s_add_u32 s100, s84, 0x8f00000
	s_addc_u32 s101, s85, 0
	s_waitcnt vmcnt(0) lgkmcnt(0)
	ds_read_b32 v2, v71
	ds_read_b32 v3, v71 offset:260
	ds_read_b32 v4, v71 offset:520
	ds_read_b32 v5, v71 offset:780
	ds_read_b32 v6, v71 offset:1040
	ds_read_b32 v7, v71 offset:1300
	ds_read_b32 v8, v71 offset:1560
	ds_read_b32 v9, v71 offset:1820
	ds_read_b32 v10, v71 offset:32
	ds_read_b32 v11, v71 offset:292
	ds_read_b32 v12, v71 offset:552
	ds_read_b32 v13, v71 offset:812
	ds_read_b32 v14, v71 offset:1072
	ds_read_b32 v15, v71 offset:1332
	ds_read_b32 v16, v71 offset:1592
	ds_read_b32 v17, v71 offset:1852
	ds_read_b32 v18, v71 offset:64
	ds_read_b32 v19, v71 offset:324
	ds_read_b32 v20, v71 offset:584
	ds_read_b32 v21, v71 offset:844
	ds_read_b32 v22, v71 offset:1104
	ds_read_b32 v23, v71 offset:1364
	ds_read_b32 v24, v71 offset:1624
	ds_read_b32 v25, v71 offset:1884
	ds_read_b32 v26, v71 offset:96
	ds_read_b32 v27, v71 offset:356
	ds_read_b32 v28, v71 offset:616
	ds_read_b32 v29, v71 offset:876
	ds_read_b32 v30, v71 offset:1136
	ds_read_b32 v31, v71 offset:1396
	ds_read_b32 v32, v71 offset:1656
	ds_read_b32 v33, v71 offset:1916
	ds_read_b32 v34, v71 offset:128
	ds_read_b32 v35, v71 offset:388
	ds_read_b32 v36, v71 offset:648
	ds_read_b32 v37, v71 offset:908
	ds_read_b32 v38, v71 offset:1168
	ds_read_b32 v39, v71 offset:1428
	ds_read_b32 v40, v71 offset:1688
	ds_read_b32 v41, v71 offset:1948
	ds_read_b32 v42, v71 offset:160
	ds_read_b32 v43, v71 offset:420
	ds_read_b32 v44, v71 offset:680
	ds_read_b32 v45, v71 offset:940
	ds_read_b32 v46, v71 offset:1200
	ds_read_b32 v47, v71 offset:1460
	ds_read_b32 v48, v71 offset:1720
	ds_read_b32 v49, v71 offset:1980
	ds_read_b32 v50, v71 offset:192
	ds_read_b32 v51, v71 offset:452
	ds_read_b32 v52, v71 offset:712
	ds_read_b32 v53, v71 offset:972
	ds_read_b32 v54, v71 offset:1232
	ds_read_b32 v55, v71 offset:1492
	ds_read_b32 v56, v71 offset:1752
	ds_read_b32 v57, v71 offset:2012
	ds_read_b32 v58, v71 offset:224
	ds_read_b32 v59, v71 offset:484
	ds_read_b32 v60, v71 offset:744
	ds_read_b32 v61, v71 offset:1004
	ds_read_b32 v62, v71 offset:1264
	ds_read_b32 v63, v71 offset:1524
	ds_read_b32 v64, v71 offset:1784
	ds_read_b32 v65, v71 offset:2044
	s_waitcnt lgkmcnt(15)
	v_mul_f32_e32 v2, v2, v74
	v_mul_f32_e32 v3, v3, v75
	v_mul_f32_e32 v4, v4, v76
	v_mul_f32_e32 v5, v5, v77
	v_mul_f32_e32 v6, v6, v78
	v_mul_f32_e32 v7, v7, v79
	v_mul_f32_e32 v8, v8, v80
	v_mul_f32_e32 v9, v9, v81
	v_cvt_pk_bf16_f32 v192, v2, v3
	v_cvt_pk_bf16_f32 v193, v4, v5
	v_cvt_pk_bf16_f32 v194, v6, v7
	v_cvt_pk_bf16_f32 v195, v8, v9
	global_store_dwordx4 v72, v[192:195], s[100:101] nt
	s_waitcnt lgkmcnt(15)
	v_mul_f32_e32 v10, v10, v74
	v_mul_f32_e32 v11, v11, v75
	v_mul_f32_e32 v12, v12, v76
	v_mul_f32_e32 v13, v13, v77
	v_mul_f32_e32 v14, v14, v78
	v_mul_f32_e32 v15, v15, v79
	v_mul_f32_e32 v16, v16, v80
	v_mul_f32_e32 v17, v17, v81
	v_cvt_pk_bf16_f32 v196, v10, v11
	v_cvt_pk_bf16_f32 v197, v12, v13
	v_cvt_pk_bf16_f32 v198, v14, v15
	v_cvt_pk_bf16_f32 v199, v16, v17
	v_add_u32_e32 v68, 0x8000, v72
	global_store_dwordx4 v68, v[196:199], s[100:101] nt
	s_waitcnt lgkmcnt(15)
	v_mul_f32_e32 v18, v18, v74
	v_mul_f32_e32 v19, v19, v75
	v_mul_f32_e32 v20, v20, v76
	v_mul_f32_e32 v21, v21, v77
	v_mul_f32_e32 v22, v22, v78
	v_mul_f32_e32 v23, v23, v79
	v_mul_f32_e32 v24, v24, v80
	v_mul_f32_e32 v25, v25, v81
	v_cvt_pk_bf16_f32 v200, v18, v19
	v_cvt_pk_bf16_f32 v201, v20, v21
	v_cvt_pk_bf16_f32 v202, v22, v23
	v_cvt_pk_bf16_f32 v203, v24, v25
	v_add_u32_e32 v67, 0x10000, v72
	global_store_dwordx4 v67, v[200:203], s[100:101] nt
	s_waitcnt lgkmcnt(15)
	v_mul_f32_e32 v26, v26, v74
	v_mul_f32_e32 v27, v27, v75
	v_mul_f32_e32 v28, v28, v76
	v_mul_f32_e32 v29, v29, v77
	v_mul_f32_e32 v30, v30, v78
	v_mul_f32_e32 v31, v31, v79
	v_mul_f32_e32 v32, v32, v80
	v_mul_f32_e32 v33, v33, v81
	v_cvt_pk_bf16_f32 v204, v26, v27
	v_cvt_pk_bf16_f32 v205, v28, v29
	v_cvt_pk_bf16_f32 v206, v30, v31
	v_cvt_pk_bf16_f32 v207, v32, v33
	v_add_u32_e32 v68, 0x18000, v72
	global_store_dwordx4 v68, v[204:207], s[100:101] nt
	s_waitcnt lgkmcnt(15)
	v_mul_f32_e32 v34, v34, v74
	v_mul_f32_e32 v35, v35, v75
	v_mul_f32_e32 v36, v36, v76
	v_mul_f32_e32 v37, v37, v77
	v_mul_f32_e32 v38, v38, v78
	v_mul_f32_e32 v39, v39, v79
	v_mul_f32_e32 v40, v40, v80
	v_mul_f32_e32 v41, v41, v81
	v_cvt_pk_bf16_f32 v208, v34, v35
	v_cvt_pk_bf16_f32 v209, v36, v37
	v_cvt_pk_bf16_f32 v210, v38, v39
	v_cvt_pk_bf16_f32 v211, v40, v41
	v_add_u32_e32 v67, 0x20000, v72
	global_store_dwordx4 v67, v[208:211], s[100:101] nt
	s_waitcnt lgkmcnt(15)
	v_mul_f32_e32 v42, v42, v74
	v_mul_f32_e32 v43, v43, v75
	v_mul_f32_e32 v44, v44, v76
	v_mul_f32_e32 v45, v45, v77
	v_mul_f32_e32 v46, v46, v78
	v_mul_f32_e32 v47, v47, v79
	v_mul_f32_e32 v48, v48, v80
	v_mul_f32_e32 v49, v49, v81
	v_cvt_pk_bf16_f32 v212, v42, v43
	v_cvt_pk_bf16_f32 v213, v44, v45
	v_cvt_pk_bf16_f32 v214, v46, v47
	v_cvt_pk_bf16_f32 v215, v48, v49
	v_add_u32_e32 v68, 0x28000, v72
	global_store_dwordx4 v68, v[212:215], s[100:101] nt
	s_waitcnt lgkmcnt(8)
	v_mul_f32_e32 v50, v50, v74
	v_mul_f32_e32 v51, v51, v75
	v_mul_f32_e32 v52, v52, v76
	v_mul_f32_e32 v53, v53, v77
	v_mul_f32_e32 v54, v54, v78
	v_mul_f32_e32 v55, v55, v79
	v_mul_f32_e32 v56, v56, v80
	v_mul_f32_e32 v57, v57, v81
	v_cvt_pk_bf16_f32 v216, v50, v51
	v_cvt_pk_bf16_f32 v217, v52, v53
	v_cvt_pk_bf16_f32 v218, v54, v55
	v_cvt_pk_bf16_f32 v219, v56, v57
	v_add_u32_e32 v67, 0x30000, v72
	global_store_dwordx4 v67, v[216:219], s[100:101] nt
	s_waitcnt lgkmcnt(0)
	v_mul_f32_e32 v58, v58, v74
	v_mul_f32_e32 v59, v59, v75
	v_mul_f32_e32 v60, v60, v76
	v_mul_f32_e32 v61, v61, v77
	v_mul_f32_e32 v62, v62, v78
	v_mul_f32_e32 v63, v63, v79
	v_mul_f32_e32 v64, v64, v80
	v_mul_f32_e32 v65, v65, v81
	v_cvt_pk_bf16_f32 v220, v58, v59
	v_cvt_pk_bf16_f32 v221, v60, v61
	v_cvt_pk_bf16_f32 v222, v62, v63
	v_cvt_pk_bf16_f32 v223, v64, v65
	v_add_u32_e32 v68, 0x38000, v72
	global_store_dwordx4 v68, v[220:223], s[100:101] nt

; #define LAS __attribute__((address_space(3)))
; #define TR_LOAD(p) __builtin_nontemporal_load(p)
; __device__ __forceinline__ TrItem tr_decode(int it, const float* const* in, unsigned char* ws, int lane) {
;     ...
;     const int rh = r >> 3, rl = r & 7, nq = ndb >> DL, kbh = rh / nq, dbh = rh - kbh * nq;
;     const int kb = (kbh << KL) + (rl >> DL), db = (dbh << DL) + (rl & ((1 << DL) - 1)), d0 = db * 64, k0 = kb * 64;
;     ...
;     const int kb = r / ndb, db = r - kb * ndb, d0 = db * 64, k0 = kb * 64;
;     ...
;     const int blk = d0 + 32 * ((lane & 15) >> 3);
;     const float* src = W; int s0 = blk;
;     if (kind == 1) { const int pn = blk >> 8, bj = (blk >> 7) & 1, o = blk & 127; src = bj ? W2 : W; s0 = pn * 128 + o; }
;     else if (kind == 2) s0 = win_src(blk);
;     TrItem t; t.src = src + (size_t)(k0 + (lane >> 4)) * N + s0 + 4 * (lane & 7); t.gain = gain ? gain + k0 + 8 * (lane & 7) : nullptr;
;     t.dst = WT + (size_t)(d0 + (lane >> 3)) * K + k0 + 8 * (lane & 7); t.N = N; t.K = K; t.nts = nts && TR_NTS;
; __device__ __forceinline__ void tr_all(const float* const* in, unsigned char* ws, LAS float* scr, int gw, int ngw, int lane, const TrRanges rg) {
;     ...
;     for (int i = 0; i < 16; ++i) v[i] = TR_LOAD((const f32x4*)(cur.src + (size_t)(4 * i) * cur.N));
;     for (int it = gw; it < TR_CNT; it += ngw) {
;         const int nit = it + ngw; const bool hn = nit < TR_CNT;
;         TrItem nx = cur; f32x4 w[16];
;         if (hn) { nx = tr_decode(rg.item(nit), in, ws, lane);
; #pragma unroll
;             for (int i = 0; i < 16; ++i) w[i] = TR_LOAD((const f32x4*)(nx.src + (size_t)(4 * i) * nx.N)); }
;         LAS float* wp = scr + (lane >> 4) * 65 + 4 * (lane & 15);
; #pragma unroll
;         for (int i = 0; i < 16; ++i) { wp[(4 * i) * 65 + 0] = v[i][0]; wp[(4 * i) * 65 + 1] = v[i][1]; wp[(4 * i) * 65 + 2] = v[i][2]; wp[(4 * i) * 65 + 3] = v[i][3]; }
.Lseam_cv_3:
	s_cmp_lt_u32 s98, 2
	s_cbranch_scc1 .LBB0_1006
	s_cmp_gt_u32 s98, 5
	s_cbranch_scc1 .LBB0_1006
	s_mov_b64 exec, -1
	s_lshl_b32 s99, s87, 2
	s_add_i32 s99, s99, s98
	s_add_i32 s99, s99, 0x11fe
	s_lshr_b32 s100, s99, 3
	s_mul_i32 s101, s100, 0x5d2
	s_lshr_b32 s101, s101, 16
	s_mul_i32 vcc_lo, s101, 44
	s_sub_i32 s100, s100, vcc_lo
	s_and_b32 vcc_lo, s99, 7
	s_lshr_b32 vcc_hi, vcc_lo, 2
	s_lshl_b32 s101, s101, 1
	s_add_i32 s101, s101, vcc_hi
	s_and_b32 vcc_lo, vcc_lo, 3
	s_lshl_b32 s100, s100, 2
	s_add_i32 s100, s100, vcc_lo
	s_lshl_b32 s101, s101, 6
	s_lshl_b32 s100, s100, 6
	v_and_b32_e32 v66, 63, v1
	v_lshrrev_b32_e32 v67, 4, v66
	v_and_b32_e32 v68, 15, v66
	v_and_b32_e32 v73, 7, v66
	v_lshrrev_b32_e32 v72, 3, v66
	s_mul_i32 s99, s98, 0x4100
	v_mul_u32_u24_e32 v70, 0x104, v67
	v_lshl_add_u32 v70, v68, 4, v70
	v_add_u32_e32 v70, s99, v70
	v_mul_u32_u24_e32 v71, 0x820, v73
	v_lshl_add_u32 v71, v72, 2, v71
	v_add_u32_e32 v71, s99, v71
	s_mul_i32 s99, s101, 0x1600
	s_lshr_b32 vcc_lo, s100, 8
	s_lshl_b32 vcc_lo, vcc_lo, 7
	s_add_i32 s99, s99, vcc_lo
	s_and_b32 vcc_lo, s100, 0x7f
	s_add_i32 s99, s99, vcc_lo
	s_lshl_b32 s99, s99, 2
	v_mul_u32_u24_e32 v69, 0x5800, v67
	v_lshl_add_u32 v69, v68, 4, v69
	v_add_u32_e32 v69, s99, v69
	s_lshl_b32 s99, s100, 12
	s_lshl_b32 vcc_lo, s101, 1
	s_add_i32 s99, s99, vcc_lo
	v_lshlrev_b32_e32 v72, 12, v72
	v_lshl_add_u32 v72, v73, 4, v72
	v_add_u32_e32 v72, s99, v72
	s_lshl_b32 s99, s101, 2
	v_lshlrev_b32_e32 v73, 5, v73
	v_add_u32_e32 v73, s99, v73
	s_nop 0
	s_bitcmp1_b32 s100, 7
	v_readlane_b32 s100, v254, 6
	v_readlane_b32 s101, v254, 7
	v_readlane_b32 s98, v254, 8
	v_readlane_b32 s99, v254, 9
	s_nop 3
	s_cselect_b32 s100, s98, s100
	s_cselect_b32 s101, s99, s101
	v_readlane_b32 s98, v254, 4
	v_readlane_b32 s99, v254, 5
	global_load_dwordx4 v[2:5], v69, s[100:101] nt
	v_add_u32_e32 v68, 0x16000, v69
	global_load_dwordx4 v[6:9], v68, s[100:101] nt
	v_add_u32_e32 v67, 0x2c000, v69
	global_load_dwordx4 v[10:13], v67, s[100:101] nt
	v_add_u32_e32 v68, 0x42000, v69
	global_load_dwordx4 v[14:17], v68, s[100:101] nt
	v_add_u32_e32 v67, 0x58000, v69
	global_load_dwordx4 v[18:21], v67, s[100:101] nt
	v_add_u32_e32 v68, 0x6e000, v69
	global_load_dwordx4 v[22:25], v68, s[100:101] nt
	v_add_u32_e32 v67, 0x84000, v69
	global_load_dwordx4 v[26:29], v67, s[100:101] nt
	v_add_u32_e32 v68, 0x9a000, v69
	global_load_dwordx4 v[30:33], v68, s[100:101] nt
	v_add_u32_e32 v67, 0xb0000, v69
	global_load_dwordx4 v[34:37], v67, s[100:101] nt
	v_add_u32_e32 v68, 0xc6000, v69
	global_load_dwordx4 v[38:41], v68, s[100:101] nt
	v_add_u32_e32 v67, 0xdc000, v69
	global_load_dwordx4 v[42:45], v67, s[100:101] nt
	v_add_u32_e32 v68, 0xf2000, v69
	global_load_dwordx4 v[46:49], v68, s[100:101] nt
	v_add_u32_e32 v67, 0x108000, v69
	global_load_dwordx4 v[50:53], v67, s[100:101] nt
	v_add_u32_e32 v68, 0x11e000, v69
	global_load_dwordx4 v[54:57], v68, s[100:101] nt
	v_add_u32_e32 v67, 0x134000, v69
	global_load_dwordx4 v[58:61], v67, s[100:101] nt
	v_add_u32_e32 v68, 0x14a000, v69
	global_load_dwordx4 v[62:65], v68, s[100:101] nt
	global_load_dwordx4 v[74:77], v73, s[98:99]
	global_load_dwordx4 v[78:81], v73, s[98:99] offset:16
	s_waitcnt vmcnt(17)
	ds_write_b32 v70, v2
	ds_write_b32 v70, v3 offset:4
	ds_write_b32 v70, v4 offset:8
	ds_write_b32 v70, v5 offset:12
	s_waitcnt vmcnt(16)
	ds_write_b32 v70, v6 offset:1040
	ds_write_b32 v70, v7 offset:1044
	ds_write_b32 v70, v8 offset:1048
	ds_write_b32 v70, v9 offset:1052
	s_waitcnt vmcnt(15)
	ds_write_b32 v70, v10 offset:2080
	ds_write_b32 v70, v11 offset:2084
	ds_write_b32 v70, v12 offset:2088
	ds_write_b32 v70, v13 offset:2092
	s_waitcnt vmcnt(14)
	ds_write_b32 v70, v14 offset:3120
	ds_write_b32 v70, v15 offset:3124
	ds_write_b32 v70, v16 offset:3128
	ds_write_b32 v70, v17 offset:3132
	s_waitcnt vmcnt(13)
	ds_write_b32 v70, v18 offset:4160
	ds_write_b32 v70, v19 offset:4164
	ds_write_b32 v70, v20 offset:4168
	ds_write_b32 v70, v21 offset:4172
	s_waitcnt vmcnt(12)
	ds_write_b32 v70, v22 offset:5200
	ds_write_b32 v70, v23 offset:5204
	ds_write_b32 v70, v24 offset:5208
	ds_write_b32 v70, v25 offset:5212
	s_waitcnt vmcnt(11)
	ds_write_b32 v70, v26 offset:6240
	ds_write_b32 v70, v27 offset:6244
	ds_write_b32 v70, v28 offset:6248
	ds_write_b32 v70, v29 offset:6252
	s_waitcnt vmcnt(10)
	ds_write_b32 v70, v30 offset:7280
	ds_write_b32 v70, v31 offset:7284
	ds_write_b32 v70, v32 offset:7288
	ds_write_b32 v70, v33 offset:7292
	s_waitcnt vmcnt(9)
	ds_write_b32 v70, v34 offset:8320
	ds_write_b32 v70, v35 offset:8324
	ds_write_b32 v70, v36 offset:8328
	ds_write_b32 v70, v37 offset:8332
	s_waitcnt vmcnt(8)
	ds_write_b32 v70, v38 offset:9360
	ds_write_b32 v70, v39 offset:9364
	ds_write_b32 v70, v40 offset:9368
	ds_write_b32 v70, v41 offset:9372
	s_waitcnt vmcnt(7)
	ds_write_b32 v70, v42 offset:10400
	ds_write_b32 v70, v43 offset:10404
	ds_write_b32 v70, v44 offset:10408
	ds_write_b32 v70, v45 offset:10412
	s_waitcnt vmcnt(6)
	ds_write_b32 v70, v46 offset:11440
	ds_write_b32 v70, v47 offset:11444
	ds_write_b32 v70, v48 offset:11448
	ds_write_b32 v70, v49 offset:11452
	s_waitcnt vmcnt(5)
	ds_write_b32 v70, v50 offset:12480
	ds_write_b32 v70, v51 offset:12484
	ds_write_b32 v70, v52 offset:12488
	ds_write_b32 v70, v53 offset:12492
	s_waitcnt vmcnt(4)
	ds_write_b32 v70, v54 offset:13520
	ds_write_b32 v70, v55 offset:13524
	ds_write_b32 v70, v56 offset:13528
	ds_write_b32 v70, v57 offset:13532
	s_waitcnt vmcnt(3)
	ds_write_b32 v70, v58 offset:14560
	ds_write_b32 v70, v59 offset:14564
	ds_write_b32 v70, v60 offset:14568
	ds_write_b32 v70, v61 offset:14572
	s_waitcnt vmcnt(2)
; #define LAS __attribute__((address_space(3)))
; __device__ __forceinline__ unsigned cvtpk(float lo, float hi) { f32x2_t v = {lo, hi}; bf16x2_t b = __builtin_convertvector(v, bf16x2_t); return __builtin_bit_cast(unsigned, b); }
; __device__ __forceinline__ void tr_all(const float* const* in, unsigned char* ws, LAS float* scr, int gw, int ngw, int lane, const TrRanges rg) {
;     ...
;         for (int i = 0; i < 16; ++i) { wp[(4 * i) * 65 + 0] = v[i][0]; wp[(4 * i) * 65 + 1] = v[i][1]; wp[(4 * i) * 65 + 2] = v[i][2]; wp[(4 * i) * 65 + 3] = v[i][3]; }
;         f32x4 g0 = {1.f, 1.f, 1.f, 1.f}, g1 = {1.f, 1.f, 1.f, 1.f};
;         if (cur.gain) { g0 = *(const f32x4*)cur.gain; g1 = *(const f32x4*)(cur.gain + 4); }
;         asm volatile("s_waitcnt lgkmcnt(0)" ::: "memory");
;         const LAS float* rp = scr + (8 * (lane & 7)) * 65 + (lane >> 3);
; #pragma unroll
;         for (int j = 0; j < 8; ++j) { const LAS float* s = rp + 8 * j;
;             u32x4 o; o.x = cvtpk(s[0 * 65] * g0[0], s[1 * 65] * g0[1]); o.y = cvtpk(s[2 * 65] * g0[2], s[3 * 65] * g0[3]);
;             o.z = cvtpk(s[4 * 65] * g1[0], s[5 * 65] * g1[1]); o.w = cvtpk(s[6 * 65] * g1[2], s[7 * 65] * g1[3]);
;             if (cur.nts) __builtin_nontemporal_store(o, (u32x4*)(cur.dst + (size_t)(8 * j) * cur.K)); else *(u32x4*)(cur.dst + (size_t)(8 * j) * cur.K) = o; }
	ds_write_b32 v70, v62 offset:15600
	ds_write_b32 v70, v63 offset:15604
	ds_write_b32 v70, v64 offset:15608
	ds_write_b32 v70, v65 offset:15612
	s_add_u32 s100, s84, 0x8f00000
	s_addc_u32 s101, s85, 0
	s_waitcnt vmcnt(0) lgkmcnt(0)
	ds_read_b32 v2, v71
	ds_read_b32 v3, v71 offset:260
	ds_read_b32 v4, v71 offset:520
	ds_read_b32 v5, v71 offset:780
	ds_read_b32 v6, v71 offset:1040
	ds_read_b32 v7, v71 offset:1300
	ds_read_b32 v8, v71 offset:1560
	ds_read_b32 v9, v71 offset:1820
	ds_read_b32 v10, v71 offset:32
	ds_read_b32 v11, v71 offset:292
	ds_read_b32 v12, v71 offset:552
	ds_read_b32 v13, v71 offset:812
	ds_read_b32 v14, v71 offset:1072
	ds_read_b32 v15, v71 offset:1332
	ds_read_b32 v16, v71 offset:1592
	ds_read_b32 v17, v71 offset:1852
	ds_read_b32 v18, v71 offset:64
	ds_read_b32 v19, v71 offset:324
	ds_read_b32 v20, v71 offset:584
	ds_read_b32 v21, v71 offset:844
	ds_read_b32 v22, v71 offset:1104
	ds_read_b32 v23, v71 offset:1364
	ds_read_b32 v24, v71 offset:1624
	ds_read_b32 v25, v71 offset:1884
	ds_read_b32 v26, v71 offset:96
	ds_read_b32 v27, v71 offset:356
	ds_read_b32 v28, v71 offset:616
	ds_read_b32 v29, v71 offset:876
	ds_read_b32 v30, v71 offset:1136
	ds_read_b32 v31, v71 offset:1396
	ds_read_b32 v32, v71 offset:1656
	ds_read_b32 v33, v71 offset:1916
	ds_read_b32 v34, v71 offset:128
	ds_read_b32 v35, v71 offset:388
	ds_read_b32 v36, v71 offset:648
	ds_read_b32 v37, v71 offset:908
	ds_read_b32 v38, v71 offset:1168
	ds_read_b32 v39, v71 offset:1428
	ds_read_b32 v40, v71 offset:1688
	ds_read_b32 v41, v71 offset:1948
	ds_read_b32 v42, v71 offset:160
	ds_read_b32 v43, v71 offset:420
	ds_read_b32 v44, v71 offset:680
	ds_read_b32 v45, v71 offset:940
	ds_read_b32 v46, v71 offset:1200
	ds_read_b32 v47, v71 offset:1460
	ds_read_b32 v48, v71 offset:1720
	ds_read_b32 v49, v71 offset:1980
	ds_read_b32 v50, v71 offset:192
	ds_read_b32 v51, v71 offset:452
	ds_read_b32 v52, v71 offset:712
	ds_read_b32 v53, v71 offset:972
	ds_read_b32 v54, v71 offset:1232
	ds_read_b32 v55, v71 offset:1492
	ds_read_b32 v56, v71 offset:1752
	ds_read_b32 v57, v71 offset:2012
	ds_read_b32 v58, v71 offset:224
	ds_read_b32 v59, v71 offset:484
	ds_read_b32 v60, v71 offset:744
	ds_read_b32 v61, v71 offset:1004
	ds_read_b32 v62, v71 offset:1264
	ds_read_b32 v63, v71 offset:1524
	ds_read_b32 v64, v71 offset:1784
	ds_read_b32 v65, v71 offset:2044
	s_waitcnt lgkmcnt(15)
	v_mul_f32_e32 v2, v2, v74
	v_mul_f32_e32 v3, v3, v75
	v_mul_f32_e32 v4, v4, v76
	v_mul_f32_e32 v5, v5, v77
	v_mul_f32_e32 v6, v6, v78
	v_mul_f32_e32 v7, v7, v79
	v_mul_f32_e32 v8, v8, v80
	v_mul_f32_e32 v9, v9, v81
	v_cvt_pk_bf16_f32 v192, v2, v3
	v_cvt_pk_bf16_f32 v193, v4, v5
	v_cvt_pk_bf16_f32 v194, v6, v7
	v_cvt_pk_bf16_f32 v195, v8, v9
	global_store_dwordx4 v72, v[192:195], s[100:101] nt
	s_waitcnt lgkmcnt(15)
	v_mul_f32_e32 v10, v10, v74
	v_mul_f32_e32 v11, v11, v75
	v_mul_f32_e32 v12, v12, v76
	v_mul_f32_e32 v13, v13, v77
	v_mul_f32_e32 v14, v14, v78
	v_mul_f32_e32 v15, v15, v79
	v_mul_f32_e32 v16, v16, v80
	v_mul_f32_e32 v17, v17, v81
	v_cvt_pk_bf16_f32 v196, v10, v11
	v_cvt_pk_bf16_f32 v197, v12, v13
	v_cvt_pk_bf16_f32 v198, v14, v15
	v_cvt_pk_bf16_f32 v199, v16, v17
	v_add_u32_e32 v68, 0x8000, v72
	global_store_dwordx4 v68, v[196:199], s[100:101] nt
	s_waitcnt lgkmcnt(15)
	v_mul_f32_e32 v18, v18, v74
	v_mul_f32_e32 v19, v19, v75
	v_mul_f32_e32 v20, v20, v76
	v_mul_f32_e32 v21, v21, v77
	v_mul_f32_e32 v22, v22, v78
	v_mul_f32_e32 v23, v23, v79
	v_mul_f32_e32 v24, v24, v80
	v_mul_f32_e32 v25, v25, v81
	v_cvt_pk_bf16_f32 v200, v18, v19
	v_cvt_pk_bf16_f32 v201, v20, v21
	v_cvt_pk_bf16_f32 v202, v22, v23
	v_cvt_pk_bf16_f32 v203, v24, v25
	v_add_u32_e32 v67, 0x10000, v72
	global_store_dwordx4 v67, v[200:203], s[100:101] nt
	s_waitcnt lgkmcnt(15)
	v_mul_f32_e32 v26, v26, v74
	v_mul_f32_e32 v27, v27, v75
	v_mul_f32_e32 v28, v28, v76
	v_mul_f32_e32 v29, v29, v77
	v_mul_f32_e32 v30, v30, v78
	v_mul_f32_e32 v31, v31, v79
	v_mul_f32_e32 v32, v32, v80
	v_mul_f32_e32 v33, v33, v81
	v_cvt_pk_bf16_f32 v204, v26, v27
	v_cvt_pk_bf16_f32 v205, v28, v29
	v_cvt_pk_bf16_f32 v206, v30, v31
	v_cvt_pk_bf16_f32 v207, v32, v33
	v_add_u32_e32 v68, 0x18000, v72
	global_store_dwordx4 v68, v[204:207], s[100:101] nt
	s_waitcnt lgkmcnt(15)
	v_mul_f32_e32 v34, v34, v74
	v_mul_f32_e32 v35, v35, v75
	v_mul_f32_e32 v36, v36, v76
	v_mul_f32_e32 v37, v37, v77
	v_mul_f32_e32 v38, v38, v78
	v_mul_f32_e32 v39, v39, v79
	v_mul_f32_e32 v40, v40, v80
	v_mul_f32_e32 v41, v41, v81
	v_cvt_pk_bf16_f32 v208, v34, v35
	v_cvt_pk_bf16_f32 v209, v36, v37
	v_cvt_pk_bf16_f32 v210, v38, v39
	v_cvt_pk_bf16_f32 v211, v40, v41
	v_add_u32_e32 v67, 0x20000, v72
	global_store_dwordx4 v67, v[208:211], s[100:101] nt
	s_waitcnt lgkmcnt(15)
	v_mul_f32_e32 v42, v42, v74
	v_mul_f32_e32 v43, v43, v75
	v_mul_f32_e32 v44, v44, v76
	v_mul_f32_e32 v45, v45, v77
	v_mul_f32_e32 v46, v46, v78
	v_mul_f32_e32 v47, v47, v79
	v_mul_f32_e32 v48, v48, v80
	v_mul_f32_e32 v49, v49, v81
	v_cvt_pk_bf16_f32 v212, v42, v43
	v_cvt_pk_bf16_f32 v213, v44, v45
	v_cvt_pk_bf16_f32 v214, v46, v47
	v_cvt_pk_bf16_f32 v215, v48, v49
	v_add_u32_e32 v68, 0x28000, v72
	global_store_dwordx4 v68, v[212:215], s[100:101] nt
	s_waitcnt lgkmcnt(8)
	v_mul_f32_e32 v50, v50, v74
	v_mul_f32_e32 v51, v51, v75
	v_mul_f32_e32 v52, v52, v76
	v_mul_f32_e32 v53, v53, v77
	v_mul_f32_e32 v54, v54, v78
	v_mul_f32_e32 v55, v55, v79
	v_mul_f32_e32 v56, v56, v80
	v_mul_f32_e32 v57, v57, v81
	v_cvt_pk_bf16_f32 v216, v50, v51
	v_cvt_pk_bf16_f32 v217, v52, v53
	v_cvt_pk_bf16_f32 v218, v54, v55
	v_cvt_pk_bf16_f32 v219, v56, v57
	v_add_u32_e32 v67, 0x30000, v72
	global_store_dwordx4 v67, v[216:219], s[100:101] nt
	s_waitcnt lgkmcnt(0)
	v_mul_f32_e32 v58, v58, v74
	v_mul_f32_e32 v59, v59, v75
	v_mul_f32_e32 v60, v60, v76
	v_mul_f32_e32 v61, v61, v77
	v_mul_f32_e32 v62, v62, v78
	v_mul_f32_e32 v63, v63, v79
	v_mul_f32_e32 v64, v64, v80
	v_mul_f32_e32 v65, v65, v81
	v_cvt_pk_bf16_f32 v220, v58, v59
	v_cvt_pk_bf16_f32 v221, v60, v61
	v_cvt_pk_bf16_f32 v222, v62, v63
	v_cvt_pk_bf16_f32 v223, v64, v65
	v_add_u32_e32 v68, 0x38000, v72
	global_store_dwordx4 v68, v[220:223], s[100:101] nt
